# staging waves: cumulative hand-off chain for the running decay sum (each wave waits only for its predecessor and publishes the running sum through its own block): fewer flag/total reads and adds per i
# speedup vs baseline: 1.0064x; 1.0064x over previous
.Lsc_G:
	v_add_u32_e32 v1, 0xffffff00, v173
	v_lshrrev_b32_e32 v2, 3, v1
	v_and_b32_e32 v3, 7, v1
	s_and_b32 s8, s4, 7
	s_bfe_u32 s10, s4, 0x20003
	s_lshr_b32 s11, s4, 7
	s_bfe_u32 s9, s4, 0x20005
	s_lshl_b32 s9, s9, 13
	v_readlane_b32 s50, v242, 0
	v_readlane_b32 s51, v242, 1
	v_readlane_b32 s16, v242, 62
	s_load_dwordx4 s[12:15], s[50:51], 0x68
	s_add_u32 s36, s90, 0x5e00000
	s_addc_u32 s37, s91, 0
	s_add_u32 s38, s90, 0x7e00000
	s_addc_u32 s39, s91, 0
	s_add_u32 s44, s90, 0x9e00000
	s_addc_u32 s45, s91, 0
	s_add_u32 s46, s90, 0x1c00000
	s_addc_u32 s47, s91, 0
	s_lshl_b32 s68, s11, 25
	s_add_u32 s69, s68, 0x13e00000
	s_add_u32 s40, s90, s69
	s_addc_u32 s41, s91, 0
	s_add_u32 s69, s68, 0x17e00000
	s_add_u32 s42, s90, s69
	s_addc_u32 s43, s91, 0
	s_lshl_b32 s68, s11, 26
	s_add_u32 s68, s68, 0xbe00000
	s_add_u32 s48, s90, s68
	s_addc_u32 s49, s91, 0
	s_cmp_eq_u32 s11, 0
	s_mov_b32 s54, 0x8000
	s_movk_i32 s55, 0x400
	s_mov_b32 s64, 0x10000
	s_cselect_b32 s54, s54, 0xffff8000
	s_cselect_b32 s55, s55, 0xfffffc00
	s_cselect_b32 s64, s64, 0xffff0000
	s_cselect_b64 vcc, -1, 0
	v_sub_u32_e32 v4, 0x1fff, v2
	s_nop 3
	v_cndmask_b32_e32 v4, v4, v2, vcc
	v_add_u32_e32 v4, s9, v4
	s_lshl_b32 s68, s8, 7
	v_lshlrev_b32_e32 v5, 10, v4
	v_lshl_add_u32 v5, v3, 3, v5
	v_add_u32_e32 v5, s68, v5
	s_lshl_b32 s69, s8, 2
	v_lshlrev_b32_e32 v6, 5, v4
	v_add_u32_e32 v6, s69, v6
	s_lshl_b32 s69, s10, 5
	s_add_i32 s69, s69, s68
	v_lshlrev_b32_e32 v9, 10, v4
	v_lshl_add_u32 v9, v3, 2, v9
	v_add_u32_e32 v9, s69, v9
	s_lshl_b32 s65, s69, 1
	v_mul_u32_u24_e32 v8, 1024, v2
	v_lshl_add_u32 v8, v3, 4, v8
	v_add_u32_e32 v138, 512, v8
	v_add_u32_e32 v140, 35328, v8
	v_add_u32_e32 v152, -4, v0
	v_mul_u32_u24_e32 v152, 4608, v152
	v_add_u32_e32 v152, 143936, v152
	v_and_b32_e32 v156, 7, v2
	v_lshlrev_b32_e32 v153, 8, v156
	v_lshl_add_u32 v153, v3, 4, v153
	v_add_u32_e32 v153, v152, v153
	v_and_b32_e32 v154, 63, v1
	v_lshl_add_u32 v154, v154, 2, v152
	v_add_u32_e32 v155, 2048, v154
	v_add_u32_e32 v139, -1, v2
	v_mul_u32_u24_e32 v139, 1024, v139
	v_lshl_add_u32 v139, v3, 4, v139
	v_add_u32_e32 v141, 35328, v139
	v_add_u32_e32 v139, 512, v139
	v_cmp_eq_u32_e32 vcc, 0, v2
	s_nop 1
	v_cndmask_b32_e32 v139, v139, v152, vcc
	v_cndmask_b32_e32 v141, v141, v152, vcc
	v_lshrrev_b32_e32 v158, 3, v2
	v_lshlrev_b32_e32 v158, 8, v158
	v_lshl_add_u32 v158, v3, 4, v158
	v_and_b32_e32 v159, 63, v1
	v_lshlrev_b32_e32 v159, 2, v159
	v_add_u32_e32 v106, -4, v0
	v_lshl_add_u32 v159, v106, 8, v159
	v_add_u32_e32 v159, 33792, v159
	v_add_u32_e32 v106, -4, v0
	v_lshlrev_b32_e32 v162, 2, v106
	v_add_u32_e32 v162, 139808, v162
	v_mov_b32_e32 v163, 139808
	v_and_b32_e32 v181, 63, v1
	v_lshlrev_b32_e32 v181, 2, v181
	v_add_u32_e32 v181, 139840, v181
	v_lshl_add_u32 v180, v106, 8, v181
	v_cmp_gt_u32_e32 vcc, v106, v169
	s_nop 1
	v_cndmask_b32_e64 v174, 0, -1, vcc
	v_mov_b32_e32 v177, 0x7fffffff
	v_cndmask_b32_e32 v177, v177, v169, vcc
	v_cmp_lt_u32_e32 vcc, 1, v106
	s_nop 1
	v_cndmask_b32_e64 v175, 0, -1, vcc
	v_mov_b32_e32 v178, 0x7fffffff
	v_cndmask_b32_e32 v178, v178, v169, vcc
	v_cmp_lt_u32_e32 vcc, 2, v106
	s_nop 1
	v_cndmask_b32_e64 v176, 0, -1, vcc
	v_mov_b32_e32 v179, 0x7fffffff
	v_cndmask_b32_e32 v179, v179, v169, vcc
	v_cmp_lt_u32_e32 vcc, 0, v106
	v_add_u32_e32 v175, 0xffffff00, v180
	v_add_u32_e32 v163, -4, v162
	s_nop 1
	v_cndmask_b32_e32 v175, v181, v175, vcc
	v_cndmask_b32_e32 v163, v162, v163, vcc
	v_add_u32_e32 v158, 32768, v158
	v_mul_u32_u24_e32 v142, 288, v3
	v_lshl_add_u32 v142, v2, 2, v142
	v_add_u32_e32 v143, 71936, v142
	v_add_u32_e32 v142, 69632, v142
	s_lshl_b32 s69, s8, 6
	s_add_i32 s69, s69, s16
	v_lshl_add_u32 v106, v3, 2, s69
	v_lshlrev_b32_e32 v106, 2, v106
	s_waitcnt lgkmcnt(0)
	global_load_dwordx4 v[12:15], v106, s[12:13]
	global_load_dwordx4 v[16:19], v106, s[12:13] offset:128
	global_load_dwordx4 v[20:23], v106, s[14:15]
	global_load_dwordx4 v[24:27], v106, s[14:15] offset:128
	global_load_dwordx2 v[28:29], v5, s[36:37]
	global_load_dwordx2 v[30:31], v5, s[36:37] offset:64
	global_load_dwordx2 v[32:33], v5, s[38:39]
	global_load_dwordx2 v[34:35], v5, s[38:39] offset:64
	global_load_dwordx2 v[36:37], v5, s[40:41]
	global_load_dwordx2 v[38:39], v5, s[40:41] offset:64
	global_load_dwordx2 v[40:41], v5, s[42:43]
	global_load_dwordx2 v[42:43], v5, s[42:43] offset:64
	global_load_dword v44, v6, s[46:47]
	global_load_dword v45, v9, s[44:45]
	v_add_u32_e32 v5, s54, v5
	v_add_u32_e32 v6, s55, v6
	v_add_u32_e32 v9, s54, v9
	global_load_dwordx2 v[46:47], v5, s[36:37]
	global_load_dwordx2 v[48:49], v5, s[36:37] offset:64
	global_load_dwordx2 v[50:51], v5, s[38:39]
	global_load_dwordx2 v[52:53], v5, s[38:39] offset:64
	global_load_dwordx2 v[54:55], v5, s[40:41]
	global_load_dwordx2 v[56:57], v5, s[40:41] offset:64
	global_load_dwordx2 v[58:59], v5, s[42:43]
	global_load_dwordx2 v[60:61], v5, s[42:43] offset:64
	global_load_dword v62, v6, s[46:47]
	global_load_dword v63, v9, s[44:45]
	v_add_u32_e32 v5, s54, v5
	v_add_u32_e32 v6, s55, v6
	v_add_u32_e32 v9, s54, v9
	v_and_b32_e32 v166, 15, v1
	v_lshrrev_b32_e32 v167, 4, v1
	v_sub_u32_e32 v4, 0x1fff, v167
	s_cmp_eq_u32 s11, 0
	s_cselect_b64 vcc, -1, 0
	s_nop 3
	v_cndmask_b32_e32 v4, v4, v167, vcc
	v_add_u32_e32 v4, s9, v4
	v_lshlrev_b32_e32 v7, 11, v4
	v_lshl_add_u32 v7, v166, 2, v7
	v_add_u32_e32 v7, s65, v7
	s_ashr_i32 s65, s64, 1
	v_add_u32_e32 v165, s65, v7
	v_lshlrev_b32_e32 v11, 10, v167
	v_lshl_add_u32 v11, v166, 6, v11
	v_add_u32_e32 v11, 74240, v11
	v_lshrrev_b32_e32 v166, 2, v166
	v_add_u32_e32 v2, 0, v166
	v_and_b32_e32 v2, 3, v2
	v_lshl_add_u32 v2, v2, 4, v11
	v_add_u32_e32 v3, 1, v166
	v_and_b32_e32 v3, 3, v3
	v_lshl_add_u32 v3, v3, 4, v11
	v_add_u32_e32 v4, 2, v166
	v_and_b32_e32 v4, 3, v4
	v_lshl_add_u32 v4, v4, 4, v11
	v_add_u32_e32 v10, 3, v166
	v_and_b32_e32 v10, 3, v10
	v_lshl_add_u32 v10, v10, 4, v11
	s_waitcnt vmcnt(20)
	v_pk_add_f32 v[190:191], v[20:21], 1.0 op_sel_hi:[1,0] neg_lo:[1,0] neg_hi:[1,0]
	v_pk_add_f32 v[192:193], v[22:23], 1.0 op_sel_hi:[1,0] neg_lo:[1,0] neg_hi:[1,0]
	v_pk_add_f32 v[194:195], v[24:25], 1.0 op_sel_hi:[1,0] neg_lo:[1,0] neg_hi:[1,0]
	v_pk_add_f32 v[196:197], v[26:27], 1.0 op_sel_hi:[1,0] neg_lo:[1,0] neg_hi:[1,0]
	v_cmp_eq_u32_e64 s[12:13], 0, v156
	s_mov_b32 s14, 0x3fb8aa3b
	s_mov_b32 s6, 0
	v_mov_b32_e32 v144, 139792
	v_mov_b32_e32 v145, v164
	v_mov_b32_e32 v146, 0
	s_waitcnt vmcnt(10)
	v_lshlrev_b32_e32 v64, 16, v36
	v_and_b32_e32 v65, 0xffff0000, v36
	v_lshlrev_b32_e32 v66, 16, v37
	v_and_b32_e32 v67, 0xffff0000, v37
	v_lshlrev_b32_e32 v68, 16, v38
	v_and_b32_e32 v69, 0xffff0000, v38
	v_lshlrev_b32_e32 v70, 16, v39
	v_and_b32_e32 v71, 0xffff0000, v39
	ds_write_b128 v153, v[64:67]
	ds_write_b128 v153, v[68:71] offset:128
	s_waitcnt lgkmcnt(0)
	ds_read_b32 v124, v154 offset:0
	ds_read_b32 v125, v154 offset:256
	ds_read_b32 v126, v154 offset:512
	ds_read_b32 v127, v154 offset:768
	ds_read_b32 v128, v154 offset:1024
	ds_read_b32 v129, v154 offset:1280
	ds_read_b32 v130, v154 offset:1536
	ds_read_b32 v131, v154 offset:1792
	v_lshlrev_b32_e32 v108, 16, v32
	v_and_b32_e32 v109, 0xffff0000, v32
	v_lshlrev_b32_e32 v110, 16, v40
	v_and_b32_e32 v111, 0xffff0000, v40
	v_lshlrev_b32_e32 v96, 16, v28
	v_and_b32_e32 v97, 0xffff0000, v28
	v_pk_mul_f32 v[114:115], v[12:13], v[108:109]
	v_pk_fma_f32 v[112:113], v[20:21], v[110:111], v[190:191]
	v_pk_mul_f32 v[88:89], v[44:45], v[114:115] op_sel_hi:[0,1]
	v_pk_mul_f32 v[72:73], v[112:113], v[108:109]
	v_pk_mul_f32 v[80:81], v[88:89], v[110:111]
	v_lshlrev_b32_e32 v108, 16, v33
	v_and_b32_e32 v109, 0xffff0000, v33
	v_lshlrev_b32_e32 v110, 16, v41
	v_and_b32_e32 v111, 0xffff0000, v41
	v_lshlrev_b32_e32 v98, 16, v29
	v_and_b32_e32 v99, 0xffff0000, v29
	v_pk_mul_f32 v[114:115], v[14:15], v[108:109]
	v_pk_fma_f32 v[112:113], v[22:23], v[110:111], v[192:193]
	v_pk_mul_f32 v[90:91], v[44:45], v[114:115] op_sel_hi:[0,1]
	v_pk_mul_f32 v[74:75], v[112:113], v[108:109]
	v_pk_mul_f32 v[82:83], v[90:91], v[110:111]
	v_lshlrev_b32_e32 v108, 16, v34
	v_and_b32_e32 v109, 0xffff0000, v34
	v_lshlrev_b32_e32 v110, 16, v42
	v_and_b32_e32 v111, 0xffff0000, v42
	v_lshlrev_b32_e32 v100, 16, v30
	v_and_b32_e32 v101, 0xffff0000, v30
	v_pk_mul_f32 v[114:115], v[16:17], v[108:109]
	v_pk_fma_f32 v[112:113], v[24:25], v[110:111], v[194:195]
	v_pk_mul_f32 v[92:93], v[44:45], v[114:115] op_sel_hi:[0,1]
	v_pk_mul_f32 v[76:77], v[112:113], v[108:109]
	v_pk_mul_f32 v[84:85], v[92:93], v[110:111]
	v_lshlrev_b32_e32 v108, 16, v35
	v_and_b32_e32 v109, 0xffff0000, v35
	v_lshlrev_b32_e32 v110, 16, v43
	v_and_b32_e32 v111, 0xffff0000, v43
	v_lshlrev_b32_e32 v102, 16, v31
	v_and_b32_e32 v103, 0xffff0000, v31
	v_pk_mul_f32 v[114:115], v[18:19], v[108:109]
	v_pk_fma_f32 v[112:113], v[26:27], v[110:111], v[196:197]
	v_pk_mul_f32 v[94:95], v[44:45], v[114:115] op_sel_hi:[0,1]
	v_pk_mul_f32 v[78:79], v[112:113], v[108:109]
	v_pk_mul_f32 v[86:87], v[94:95], v[110:111]
	v_lshlrev_b32_e32 v104, 16, v45
	v_and_b32_e32 v105, 0xffff0000, v45
	s_waitcnt lgkmcnt(0)
	v_add_f32_e32 v125, v124, v125
	v_add_f32_e32 v126, v125, v126
	v_add_f32_e32 v127, v126, v127
	v_add_f32_e32 v128, v127, v128
	v_add_f32_e32 v129, v128, v129
	v_add_f32_e32 v130, v129, v130
	v_add_f32_e32 v131, v130, v131
	s_and_b32 s72, s6, 3
	s_lshl_b32 s72, s72, 10
	v_add_u32_e32 v182, s72, v180
	v_add_u32_e32 v183, s72, v175
	v_add_u32_e32 v184, 1, v146
	s_add_u32 s73, s6, 1
	s_mov_b32 s69, 0x100000
.Lsc_gf_poll1:
	ds_read_b32 v148, v163
	s_waitcnt lgkmcnt(0)
	v_max_u32_e32 v148, v148, v177
	s_sub_u32 s69, s69, 1
	s_nop 1
	v_readfirstlane_b32 s68, v148
	s_cmp_eq_u32 s69, 0
	s_cbranch_scc1 .Lsc_gf_go1
	s_cmp_lt_u32 s68, s73
	s_cbranch_scc1 .Lsc_gf_poll1
.Lsc_gf_go1:
	ds_read_b32 v185, v183
	s_waitcnt lgkmcnt(0)
	v_and_b32_e32 v185, v174, v185
	v_fma_f32 v189, v131, s14, v185
	ds_write_b32 v182, v189
	s_waitcnt lgkmcnt(0)
	ds_write_b32 v162, v184
	v_fma_f32 v124, v124, s14, v185
	v_fma_f32 v125, v125, s14, v185
	v_fma_f32 v126, v126, s14, v185
	v_fma_f32 v127, v127, s14, v185
	v_fma_f32 v128, v128, s14, v185
	v_fma_f32 v129, v129, s14, v185
	v_fma_f32 v130, v130, s14, v185
	v_fma_f32 v131, v131, s14, v185
	v_exp_f32_e64 v188, -v185
	v_exp_f32_e64 v124, -v124
	v_exp_f32_e64 v125, -v125
	v_exp_f32_e64 v126, -v126
	v_exp_f32_e64 v127, -v127
	v_exp_f32_e64 v128, -v128
	v_exp_f32_e64 v129, -v129
	v_exp_f32_e64 v130, -v130
	v_exp_f32_e64 v131, -v131
	s_nop 0
	ds_write_b32 v155, v188
	ds_write_b32 v155, v124 offset:256
	ds_write_b32 v155, v125 offset:512
	ds_write_b32 v155, v126 offset:768
	ds_write_b32 v155, v127 offset:1024
	ds_write_b32 v155, v128 offset:1280
	ds_write_b32 v155, v129 offset:1536
	ds_write_b32 v155, v130 offset:1792
	ds_write_b32 v155, v131 offset:2048
	v_mov_b32_e32 v161, v131
	s_waitcnt lgkmcnt(0)
	ds_read_b128 v[64:67], v153 offset:2048
	ds_read_b128 v[68:71], v153 offset:2176
	ds_read_b128 v[116:119], v153 offset:2304
	ds_read_b128 v[120:123], v153 offset:2432
	s_waitcnt lgkmcnt(0)
	v_rcp_f32_e32 v124, v116
	v_rcp_f32_e32 v125, v117
	v_rcp_f32_e32 v126, v118
	v_rcp_f32_e32 v127, v119
	v_rcp_f32_e32 v128, v120
	v_rcp_f32_e32 v129, v121
	v_rcp_f32_e32 v130, v122
	v_rcp_f32_e32 v131, v123
	s_nop 1
	v_pk_mul_f32 v[72:73], v[72:73], v[124:125]
	v_pk_mul_f32 v[80:81], v[80:81], v[124:125]
	v_pk_mul_f32 v[88:89], v[88:89], v[64:65]
	v_pk_mul_f32 v[96:97], v[96:97], v[116:117]
	v_pk_mul_f32 v[74:75], v[74:75], v[126:127]
	v_pk_mul_f32 v[82:83], v[82:83], v[126:127]
	v_pk_mul_f32 v[90:91], v[90:91], v[66:67]
	v_pk_mul_f32 v[98:99], v[98:99], v[118:119]
	v_pk_mul_f32 v[76:77], v[76:77], v[128:129]
	v_pk_mul_f32 v[84:85], v[84:85], v[128:129]
	v_pk_mul_f32 v[92:93], v[92:93], v[68:69]
	v_pk_mul_f32 v[100:101], v[100:101], v[120:121]
	v_pk_mul_f32 v[78:79], v[78:79], v[130:131]
	v_pk_mul_f32 v[86:87], v[86:87], v[130:131]
	v_pk_mul_f32 v[94:95], v[94:95], v[70:71]
	v_pk_mul_f32 v[102:103], v[102:103], v[122:123]
	global_load_dwordx2 v[28:29], v5, s[36:37]
	global_load_dwordx2 v[30:31], v5, s[36:37] offset:64
	global_load_dwordx2 v[32:33], v5, s[38:39]
	global_load_dwordx2 v[34:35], v5, s[38:39] offset:64
	global_load_dwordx2 v[36:37], v5, s[40:41]
	global_load_dwordx2 v[38:39], v5, s[40:41] offset:64
	global_load_dwordx2 v[40:41], v5, s[42:43]
	global_load_dwordx2 v[42:43], v5, s[42:43] offset:64
	global_load_dword v44, v6, s[46:47]
	global_load_dword v45, v9, s[44:45]
	v_add_u32_e32 v5, s54, v5
	v_add_u32_e32 v6, s55, v6
	v_add_u32_e32 v9, s54, v9
	ds_write_b32 v159, v161 offset:0
	ds_write_b128 v8, v[72:75] offset:0
	s_sleep 1
	ds_write_b128 v8, v[76:79] offset:128
	ds_write_b128 v8, v[80:83] offset:256
	s_sleep 1
	ds_write_b128 v8, v[84:87] offset:384
	ds_write2_b32 v138, v96, v97 offset0:1 offset1:3
	s_sleep 1
	ds_write2_b32 v139, v88, v89 offset0:0 offset1:2
	ds_write2_b32 v138, v98, v99 offset0:65 offset1:67
	s_sleep 1
	ds_write2_b32 v139, v90, v91 offset0:64 offset1:66
	ds_write2_b32 v138, v100, v101 offset0:33 offset1:35
	s_sleep 1
	ds_write2_b32 v139, v92, v93 offset0:32 offset1:34
	ds_write2_b32 v138, v102, v103 offset0:97 offset1:99
	s_sleep 1
	ds_write2_b32 v139, v94, v95 offset0:96 offset1:98
	ds_write2_b32 v142, v104, v105 offset1:36
	s_sleep 1
	s_cmp_lg_u32 s7, 4
	s_cbranch_scc1 .Lsc_nokb1
	s_and_saveexec_b64 s[68:69], s[12:13]
	ds_write_b128 v158, v[88:91] offset:0
	ds_write_b128 v158, v[92:95] offset:128
	s_mov_b64 exec, s[68:69]
.Lsc_nokb1:
	s_add_i32 s6, s6, 1
	v_add_u32_e32 v146, 1, v146
	s_waitcnt lgkmcnt(0)
	ds_write_b32 v145, v146
	s_waitcnt vmcnt(10)
	v_lshlrev_b32_e32 v64, 16, v54
	v_and_b32_e32 v65, 0xffff0000, v54
	v_lshlrev_b32_e32 v66, 16, v55
	v_and_b32_e32 v67, 0xffff0000, v55
	v_lshlrev_b32_e32 v68, 16, v56
	v_and_b32_e32 v69, 0xffff0000, v56
	v_lshlrev_b32_e32 v70, 16, v57
	v_and_b32_e32 v71, 0xffff0000, v57
	ds_write_b128 v153, v[64:67]
	ds_write_b128 v153, v[68:71] offset:128
	s_waitcnt lgkmcnt(0)
	ds_read_b32 v124, v154 offset:0
	ds_read_b32 v125, v154 offset:256
	ds_read_b32 v126, v154 offset:512
	ds_read_b32 v127, v154 offset:768
	ds_read_b32 v128, v154 offset:1024
	ds_read_b32 v129, v154 offset:1280
	ds_read_b32 v130, v154 offset:1536
	ds_read_b32 v131, v154 offset:1792
	v_lshlrev_b32_e32 v108, 16, v50
	v_and_b32_e32 v109, 0xffff0000, v50
	v_lshlrev_b32_e32 v110, 16, v58
	v_and_b32_e32 v111, 0xffff0000, v58
	v_lshlrev_b32_e32 v96, 16, v46
	v_and_b32_e32 v97, 0xffff0000, v46
	v_pk_mul_f32 v[114:115], v[12:13], v[108:109]
	v_pk_fma_f32 v[112:113], v[20:21], v[110:111], v[190:191]
	v_pk_mul_f32 v[88:89], v[62:63], v[114:115] op_sel_hi:[0,1]
	v_pk_mul_f32 v[72:73], v[112:113], v[108:109]
	v_pk_mul_f32 v[80:81], v[88:89], v[110:111]
	v_lshlrev_b32_e32 v108, 16, v51
	v_and_b32_e32 v109, 0xffff0000, v51
	v_lshlrev_b32_e32 v110, 16, v59
	v_and_b32_e32 v111, 0xffff0000, v59
	v_lshlrev_b32_e32 v98, 16, v47
	v_and_b32_e32 v99, 0xffff0000, v47
	v_pk_mul_f32 v[114:115], v[14:15], v[108:109]
	v_pk_fma_f32 v[112:113], v[22:23], v[110:111], v[192:193]
	v_pk_mul_f32 v[90:91], v[62:63], v[114:115] op_sel_hi:[0,1]
	v_pk_mul_f32 v[74:75], v[112:113], v[108:109]
	v_pk_mul_f32 v[82:83], v[90:91], v[110:111]
	v_lshlrev_b32_e32 v108, 16, v52
	v_and_b32_e32 v109, 0xffff0000, v52
	v_lshlrev_b32_e32 v110, 16, v60
	v_and_b32_e32 v111, 0xffff0000, v60
	v_lshlrev_b32_e32 v100, 16, v48
	v_and_b32_e32 v101, 0xffff0000, v48
	v_pk_mul_f32 v[114:115], v[16:17], v[108:109]
	v_pk_fma_f32 v[112:113], v[24:25], v[110:111], v[194:195]
	v_pk_mul_f32 v[92:93], v[62:63], v[114:115] op_sel_hi:[0,1]
	v_pk_mul_f32 v[76:77], v[112:113], v[108:109]
	v_pk_mul_f32 v[84:85], v[92:93], v[110:111]
	v_lshlrev_b32_e32 v108, 16, v53
	v_and_b32_e32 v109, 0xffff0000, v53
	v_lshlrev_b32_e32 v110, 16, v61
	v_and_b32_e32 v111, 0xffff0000, v61
	v_lshlrev_b32_e32 v102, 16, v49
	v_and_b32_e32 v103, 0xffff0000, v49
	v_pk_mul_f32 v[114:115], v[18:19], v[108:109]
	v_pk_fma_f32 v[112:113], v[26:27], v[110:111], v[196:197]
	v_pk_mul_f32 v[94:95], v[62:63], v[114:115] op_sel_hi:[0,1]
	v_pk_mul_f32 v[78:79], v[112:113], v[108:109]
	v_pk_mul_f32 v[86:87], v[94:95], v[110:111]
	v_lshlrev_b32_e32 v104, 16, v63
	v_and_b32_e32 v105, 0xffff0000, v63
	s_waitcnt lgkmcnt(0)
	v_add_f32_e32 v125, v124, v125
	v_add_f32_e32 v126, v125, v126
	v_add_f32_e32 v127, v126, v127
	v_add_f32_e32 v128, v127, v128
	v_add_f32_e32 v129, v128, v129
	v_add_f32_e32 v130, v129, v130
	v_add_f32_e32 v131, v130, v131
	s_and_b32 s72, s6, 3
	s_lshl_b32 s72, s72, 10
	v_add_u32_e32 v182, s72, v180
	v_add_u32_e32 v183, s72, v175
	v_add_u32_e32 v184, 1, v146
	s_add_u32 s73, s6, 1
	s_mov_b32 s69, 0x100000

.Lsc_gf_go2:
	ds_read_b32 v185, v183
	s_waitcnt lgkmcnt(0)
	v_and_b32_e32 v185, v174, v185
	v_fma_f32 v189, v131, s14, v185
	ds_write_b32 v182, v189
	s_waitcnt lgkmcnt(0)
	ds_write_b32 v162, v184
	v_fma_f32 v124, v124, s14, v185
	v_fma_f32 v125, v125, s14, v185
	v_fma_f32 v126, v126, s14, v185
	v_fma_f32 v127, v127, s14, v185
	v_fma_f32 v128, v128, s14, v185
	v_fma_f32 v129, v129, s14, v185
	v_fma_f32 v130, v130, s14, v185
	v_fma_f32 v131, v131, s14, v185
	v_exp_f32_e64 v188, -v185
	v_exp_f32_e64 v124, -v124
	v_exp_f32_e64 v125, -v125
	v_exp_f32_e64 v126, -v126
	v_exp_f32_e64 v127, -v127
	v_exp_f32_e64 v128, -v128
	v_exp_f32_e64 v129, -v129
	v_exp_f32_e64 v130, -v130
	v_exp_f32_e64 v131, -v131
	s_nop 0
	ds_write_b32 v155, v188
	ds_write_b32 v155, v124 offset:256
	ds_write_b32 v155, v125 offset:512
	ds_write_b32 v155, v126 offset:768
	ds_write_b32 v155, v127 offset:1024
	ds_write_b32 v155, v128 offset:1280
	ds_write_b32 v155, v129 offset:1536
	ds_write_b32 v155, v130 offset:1792
	ds_write_b32 v155, v131 offset:2048
	v_mov_b32_e32 v161, v131
	s_waitcnt lgkmcnt(0)
	ds_read_b128 v[64:67], v153 offset:2048
	ds_read_b128 v[68:71], v153 offset:2176
	ds_read_b128 v[116:119], v153 offset:2304
	ds_read_b128 v[120:123], v153 offset:2432
	s_waitcnt lgkmcnt(0)
	v_rcp_f32_e32 v124, v116
	v_rcp_f32_e32 v125, v117
	v_rcp_f32_e32 v126, v118
	v_rcp_f32_e32 v127, v119
	v_rcp_f32_e32 v128, v120
	v_rcp_f32_e32 v129, v121
	v_rcp_f32_e32 v130, v122
	v_rcp_f32_e32 v131, v123
	s_nop 1
	v_pk_mul_f32 v[72:73], v[72:73], v[124:125]
	v_pk_mul_f32 v[80:81], v[80:81], v[124:125]
	v_pk_mul_f32 v[88:89], v[88:89], v[64:65]
	v_pk_mul_f32 v[96:97], v[96:97], v[116:117]
	v_pk_mul_f32 v[74:75], v[74:75], v[126:127]
	v_pk_mul_f32 v[82:83], v[82:83], v[126:127]
	v_pk_mul_f32 v[90:91], v[90:91], v[66:67]
	v_pk_mul_f32 v[98:99], v[98:99], v[118:119]
	v_pk_mul_f32 v[76:77], v[76:77], v[128:129]
	v_pk_mul_f32 v[84:85], v[84:85], v[128:129]
	v_pk_mul_f32 v[92:93], v[92:93], v[68:69]
	v_pk_mul_f32 v[100:101], v[100:101], v[120:121]
	v_pk_mul_f32 v[78:79], v[78:79], v[130:131]
	v_pk_mul_f32 v[86:87], v[86:87], v[130:131]
	v_pk_mul_f32 v[94:95], v[94:95], v[70:71]
	v_pk_mul_f32 v[102:103], v[102:103], v[122:123]
	global_load_dwordx2 v[46:47], v5, s[36:37]
	global_load_dwordx2 v[48:49], v5, s[36:37] offset:64
	global_load_dwordx2 v[50:51], v5, s[38:39]
	global_load_dwordx2 v[52:53], v5, s[38:39] offset:64
	global_load_dwordx2 v[54:55], v5, s[40:41]
	global_load_dwordx2 v[56:57], v5, s[40:41] offset:64
	global_load_dwordx2 v[58:59], v5, s[42:43]
	global_load_dwordx2 v[60:61], v5, s[42:43] offset:64
	global_load_dword v62, v6, s[46:47]
	global_load_dword v63, v9, s[44:45]
	v_add_u32_e32 v5, s54, v5
	v_add_u32_e32 v6, s55, v6
	v_add_u32_e32 v9, s54, v9
	ds_write_b32 v159, v161 offset:34816
	ds_write_b128 v8, v[72:75] offset:34816
	s_sleep 1
	ds_write_b128 v8, v[76:79] offset:34944
	ds_write_b128 v8, v[80:83] offset:35072
	s_sleep 1
	ds_write_b128 v8, v[84:87] offset:35200
	ds_write2_b32 v140, v96, v97 offset0:1 offset1:3
	s_sleep 1
	ds_write2_b32 v141, v88, v89 offset0:0 offset1:2
	ds_write2_b32 v140, v98, v99 offset0:65 offset1:67
	s_sleep 1
	ds_write2_b32 v141, v90, v91 offset0:64 offset1:66
	ds_write2_b32 v140, v100, v101 offset0:33 offset1:35
	s_sleep 1
	ds_write2_b32 v141, v92, v93 offset0:32 offset1:34
	ds_write2_b32 v140, v102, v103 offset0:97 offset1:99
	s_sleep 1
	ds_write2_b32 v141, v94, v95 offset0:96 offset1:98
	ds_write2_b32 v143, v104, v105 offset1:36
	s_sleep 1
	s_cmp_lg_u32 s7, 4
	s_cbranch_scc1 .Lsc_nokb2
	s_and_saveexec_b64 s[68:69], s[12:13]
	ds_write_b128 v158, v[88:91] offset:34816
	ds_write_b128 v158, v[92:95] offset:34944
	s_mov_b64 exec, s[68:69]

.Lsc_G_loop:
	s_waitcnt vmcnt(10)
	v_lshlrev_b32_e32 v64, 16, v36
	v_and_b32_e32 v65, 0xffff0000, v36
	v_lshlrev_b32_e32 v66, 16, v37
	v_and_b32_e32 v67, 0xffff0000, v37
	v_lshlrev_b32_e32 v68, 16, v38
	v_and_b32_e32 v69, 0xffff0000, v38
	v_lshlrev_b32_e32 v70, 16, v39
	v_and_b32_e32 v71, 0xffff0000, v39
	ds_write_b128 v153, v[64:67]
	ds_write_b128 v153, v[68:71] offset:128
	s_waitcnt lgkmcnt(0)
	ds_read_b32 v124, v154 offset:0
	ds_read_b32 v125, v154 offset:256
	ds_read_b32 v126, v154 offset:512
	ds_read_b32 v127, v154 offset:768
	ds_read_b32 v128, v154 offset:1024
	ds_read_b32 v129, v154 offset:1280
	ds_read_b32 v130, v154 offset:1536
	ds_read_b32 v131, v154 offset:1792
	v_lshlrev_b32_e32 v108, 16, v32
	v_and_b32_e32 v109, 0xffff0000, v32
	v_lshlrev_b32_e32 v110, 16, v40
	v_and_b32_e32 v111, 0xffff0000, v40
	v_lshlrev_b32_e32 v96, 16, v28
	v_and_b32_e32 v97, 0xffff0000, v28
	v_pk_mul_f32 v[114:115], v[12:13], v[108:109]
	v_pk_fma_f32 v[112:113], v[20:21], v[110:111], v[190:191]
	v_pk_mul_f32 v[88:89], v[44:45], v[114:115] op_sel_hi:[0,1]
	v_pk_mul_f32 v[72:73], v[112:113], v[108:109]
	v_pk_mul_f32 v[80:81], v[88:89], v[110:111]
	v_lshlrev_b32_e32 v108, 16, v33
	v_and_b32_e32 v109, 0xffff0000, v33
	v_lshlrev_b32_e32 v110, 16, v41
	v_and_b32_e32 v111, 0xffff0000, v41
	v_lshlrev_b32_e32 v98, 16, v29
	v_and_b32_e32 v99, 0xffff0000, v29
	v_pk_mul_f32 v[114:115], v[14:15], v[108:109]
	v_pk_fma_f32 v[112:113], v[22:23], v[110:111], v[192:193]
	v_pk_mul_f32 v[90:91], v[44:45], v[114:115] op_sel_hi:[0,1]
	v_pk_mul_f32 v[74:75], v[112:113], v[108:109]
	v_pk_mul_f32 v[82:83], v[90:91], v[110:111]
	v_lshlrev_b32_e32 v108, 16, v34
	v_and_b32_e32 v109, 0xffff0000, v34
	v_lshlrev_b32_e32 v110, 16, v42
	v_and_b32_e32 v111, 0xffff0000, v42
	v_lshlrev_b32_e32 v100, 16, v30
	v_and_b32_e32 v101, 0xffff0000, v30
	v_pk_mul_f32 v[114:115], v[16:17], v[108:109]
	v_pk_fma_f32 v[112:113], v[24:25], v[110:111], v[194:195]
	v_pk_mul_f32 v[92:93], v[44:45], v[114:115] op_sel_hi:[0,1]
	v_pk_mul_f32 v[76:77], v[112:113], v[108:109]
	v_pk_mul_f32 v[84:85], v[92:93], v[110:111]
	v_lshlrev_b32_e32 v108, 16, v35
	v_and_b32_e32 v109, 0xffff0000, v35
	v_lshlrev_b32_e32 v110, 16, v43
	v_and_b32_e32 v111, 0xffff0000, v43
	v_lshlrev_b32_e32 v102, 16, v31
	v_and_b32_e32 v103, 0xffff0000, v31
	v_pk_mul_f32 v[114:115], v[18:19], v[108:109]
	v_pk_fma_f32 v[112:113], v[26:27], v[110:111], v[196:197]
	v_pk_mul_f32 v[94:95], v[44:45], v[114:115] op_sel_hi:[0,1]
	v_pk_mul_f32 v[78:79], v[112:113], v[108:109]
	v_pk_mul_f32 v[86:87], v[94:95], v[110:111]
	v_lshlrev_b32_e32 v104, 16, v45
	v_and_b32_e32 v105, 0xffff0000, v45
	s_waitcnt lgkmcnt(0)
	v_add_f32_e32 v125, v124, v125
	v_add_f32_e32 v126, v125, v126
	v_add_f32_e32 v127, v126, v127
	v_add_f32_e32 v128, v127, v128
	v_add_f32_e32 v129, v128, v129
	v_add_f32_e32 v130, v129, v130
	v_add_f32_e32 v131, v130, v131
	s_and_b32 s72, s6, 3
	s_lshl_b32 s72, s72, 10
	v_add_u32_e32 v182, s72, v180
	v_add_u32_e32 v183, s72, v175
	v_add_u32_e32 v184, 1, v146
	s_add_u32 s73, s6, 1
	s_mov_b32 s69, 0x100000

.Lsc_gf_go3:
	ds_read_b32 v185, v183
	s_waitcnt lgkmcnt(0)
	v_and_b32_e32 v185, v174, v185
	v_fma_f32 v189, v131, s14, v185
	ds_write_b32 v182, v189
	s_waitcnt lgkmcnt(0)
	ds_write_b32 v162, v184
	v_fma_f32 v124, v124, s14, v185
	v_fma_f32 v125, v125, s14, v185
	v_fma_f32 v126, v126, s14, v185
	v_fma_f32 v127, v127, s14, v185
	v_fma_f32 v128, v128, s14, v185
	v_fma_f32 v129, v129, s14, v185
	v_fma_f32 v130, v130, s14, v185
	v_fma_f32 v131, v131, s14, v185
	v_exp_f32_e64 v188, -v185
	v_exp_f32_e64 v124, -v124
	v_exp_f32_e64 v125, -v125
	v_exp_f32_e64 v126, -v126
	v_exp_f32_e64 v127, -v127
	v_exp_f32_e64 v128, -v128
	v_exp_f32_e64 v129, -v129
	v_exp_f32_e64 v130, -v130
	v_exp_f32_e64 v131, -v131
	s_nop 0
	ds_write_b32 v155, v188
	ds_write_b32 v155, v124 offset:256
	ds_write_b32 v155, v125 offset:512
	ds_write_b32 v155, v126 offset:768
	ds_write_b32 v155, v127 offset:1024
	ds_write_b32 v155, v128 offset:1280
	ds_write_b32 v155, v129 offset:1536
	ds_write_b32 v155, v130 offset:1792
	ds_write_b32 v155, v131 offset:2048
	v_mov_b32_e32 v161, v131
	s_waitcnt lgkmcnt(0)
	ds_read_b128 v[64:67], v153 offset:2048
	ds_read_b128 v[68:71], v153 offset:2176
	ds_read_b128 v[116:119], v153 offset:2304
	ds_read_b128 v[120:123], v153 offset:2432
	s_waitcnt lgkmcnt(0)
	v_rcp_f32_e32 v124, v116
	v_rcp_f32_e32 v125, v117
	v_rcp_f32_e32 v126, v118
	v_rcp_f32_e32 v127, v119
	v_rcp_f32_e32 v128, v120
	v_rcp_f32_e32 v129, v121
	v_rcp_f32_e32 v130, v122
	v_rcp_f32_e32 v131, v123
	s_nop 1
	v_pk_mul_f32 v[72:73], v[72:73], v[124:125]
	v_pk_mul_f32 v[80:81], v[80:81], v[124:125]
	v_pk_mul_f32 v[88:89], v[88:89], v[64:65]
	v_pk_mul_f32 v[96:97], v[96:97], v[116:117]
	v_pk_mul_f32 v[74:75], v[74:75], v[126:127]
	v_pk_mul_f32 v[82:83], v[82:83], v[126:127]
	v_pk_mul_f32 v[90:91], v[90:91], v[66:67]
	v_pk_mul_f32 v[98:99], v[98:99], v[118:119]
	v_pk_mul_f32 v[76:77], v[76:77], v[128:129]
	v_pk_mul_f32 v[84:85], v[84:85], v[128:129]
	v_pk_mul_f32 v[92:93], v[92:93], v[68:69]
	v_pk_mul_f32 v[100:101], v[100:101], v[120:121]
	v_pk_mul_f32 v[78:79], v[78:79], v[130:131]
	v_pk_mul_f32 v[86:87], v[86:87], v[130:131]
	v_pk_mul_f32 v[94:95], v[94:95], v[70:71]
	v_pk_mul_f32 v[102:103], v[102:103], v[122:123]
	global_load_dwordx2 v[28:29], v5, s[36:37]
	global_load_dwordx2 v[30:31], v5, s[36:37] offset:64
	global_load_dwordx2 v[32:33], v5, s[38:39]
	global_load_dwordx2 v[34:35], v5, s[38:39] offset:64
	global_load_dwordx2 v[36:37], v5, s[40:41]
	global_load_dwordx2 v[38:39], v5, s[40:41] offset:64
	global_load_dwordx2 v[40:41], v5, s[42:43]
	global_load_dwordx2 v[42:43], v5, s[42:43] offset:64
	global_load_dword v44, v6, s[46:47]
	global_load_dword v45, v9, s[44:45]
	v_add_u32_e32 v5, s54, v5
	v_add_u32_e32 v6, s55, v6
	v_add_u32_e32 v9, s54, v9
	s_sub_u32 s65, s6, 1
	ds_read_b128 v[148:151], v144
	s_waitcnt lgkmcnt(0)
	v_min_u32_e32 v148, v148, v149
	v_min3_u32 v148, v148, v150, v151
	s_nop 1
	v_readfirstlane_b32 s68, v148
	s_cmp_ge_u32 s68, s65
	s_cbranch_scc1 .Lsc_G_gom0
	s_mov_b32 s69, 0x100000

.Lsc_nokb3:
	ds_read_b128 v[106:109], v2 offset:0
	ds_read_b128 v[122:125], v2 offset:16384
	s_sleep 1
	ds_read_b128 v[110:113], v3 offset:0
	ds_read_b128 v[126:129], v3 offset:16384
	s_sleep 1
	ds_read_b128 v[114:117], v4 offset:0
	ds_read_b128 v[130:133], v4 offset:16384
	s_sleep 1
	ds_read_b128 v[118:121], v10 offset:0
	ds_read_b128 v[134:137], v10 offset:16384
	s_sleep 1
	s_waitcnt lgkmcnt(0)
	v_pk_add_f32 v[106:107], v[106:107], v[108:109]
	v_pk_add_f32 v[110:111], v[110:111], v[112:113]
	v_pk_add_f32 v[114:115], v[114:115], v[116:117]
	v_pk_add_f32 v[118:119], v[118:119], v[120:121]
	v_pk_add_f32 v[106:107], v[106:107], v[110:111]
	v_pk_add_f32 v[114:115], v[114:115], v[118:119]
	v_pk_add_f32 v[106:107], v[106:107], v[114:115]
	v_add_f32_e32 v64, v106, v107
	v_pk_add_f32 v[122:123], v[122:123], v[124:125]
	v_pk_add_f32 v[126:127], v[126:127], v[128:129]
	v_pk_add_f32 v[130:131], v[130:131], v[132:133]
	v_pk_add_f32 v[134:135], v[134:135], v[136:137]
	v_pk_add_f32 v[122:123], v[122:123], v[126:127]
	v_pk_add_f32 v[130:131], v[130:131], v[134:135]
	v_pk_add_f32 v[122:123], v[122:123], v[130:131]
	v_add_f32_e32 v65, v122, v123
	global_store_dword v7, v64, s[48:49]
	global_store_dword v165, v65, s[48:49]
	v_add_u32_e32 v7, s64, v7
	v_add_u32_e32 v165, s64, v165
	s_add_i32 s6, s6, 1
	v_add_u32_e32 v146, 1, v146
	s_waitcnt lgkmcnt(0)
	ds_write_b32 v145, v146
	s_waitcnt vmcnt(10)
	v_lshlrev_b32_e32 v64, 16, v54
	v_and_b32_e32 v65, 0xffff0000, v54
	v_lshlrev_b32_e32 v66, 16, v55
	v_and_b32_e32 v67, 0xffff0000, v55
	v_lshlrev_b32_e32 v68, 16, v56
	v_and_b32_e32 v69, 0xffff0000, v56
	v_lshlrev_b32_e32 v70, 16, v57
	v_and_b32_e32 v71, 0xffff0000, v57
	ds_write_b128 v153, v[64:67]
	ds_write_b128 v153, v[68:71] offset:128
	s_waitcnt lgkmcnt(0)
	ds_read_b32 v124, v154 offset:0
	ds_read_b32 v125, v154 offset:256
	ds_read_b32 v126, v154 offset:512
	ds_read_b32 v127, v154 offset:768
	ds_read_b32 v128, v154 offset:1024
	ds_read_b32 v129, v154 offset:1280
	ds_read_b32 v130, v154 offset:1536
	ds_read_b32 v131, v154 offset:1792
	v_lshlrev_b32_e32 v108, 16, v50
	v_and_b32_e32 v109, 0xffff0000, v50
	v_lshlrev_b32_e32 v110, 16, v58
	v_and_b32_e32 v111, 0xffff0000, v58
	v_lshlrev_b32_e32 v96, 16, v46
	v_and_b32_e32 v97, 0xffff0000, v46
	v_pk_mul_f32 v[114:115], v[12:13], v[108:109]
	v_pk_fma_f32 v[112:113], v[20:21], v[110:111], v[190:191]
	v_pk_mul_f32 v[88:89], v[62:63], v[114:115] op_sel_hi:[0,1]
	v_pk_mul_f32 v[72:73], v[112:113], v[108:109]
	v_pk_mul_f32 v[80:81], v[88:89], v[110:111]
	v_lshlrev_b32_e32 v108, 16, v51
	v_and_b32_e32 v109, 0xffff0000, v51
	v_lshlrev_b32_e32 v110, 16, v59
	v_and_b32_e32 v111, 0xffff0000, v59
	v_lshlrev_b32_e32 v98, 16, v47
	v_and_b32_e32 v99, 0xffff0000, v47
	v_pk_mul_f32 v[114:115], v[14:15], v[108:109]
	v_pk_fma_f32 v[112:113], v[22:23], v[110:111], v[192:193]
	v_pk_mul_f32 v[90:91], v[62:63], v[114:115] op_sel_hi:[0,1]
	v_pk_mul_f32 v[74:75], v[112:113], v[108:109]
	v_pk_mul_f32 v[82:83], v[90:91], v[110:111]
	v_lshlrev_b32_e32 v108, 16, v52
	v_and_b32_e32 v109, 0xffff0000, v52
	v_lshlrev_b32_e32 v110, 16, v60
	v_and_b32_e32 v111, 0xffff0000, v60
	v_lshlrev_b32_e32 v100, 16, v48
	v_and_b32_e32 v101, 0xffff0000, v48
	v_pk_mul_f32 v[114:115], v[16:17], v[108:109]
	v_pk_fma_f32 v[112:113], v[24:25], v[110:111], v[194:195]
	v_pk_mul_f32 v[92:93], v[62:63], v[114:115] op_sel_hi:[0,1]
	v_pk_mul_f32 v[76:77], v[112:113], v[108:109]
	v_pk_mul_f32 v[84:85], v[92:93], v[110:111]
	v_lshlrev_b32_e32 v108, 16, v53
	v_and_b32_e32 v109, 0xffff0000, v53
	v_lshlrev_b32_e32 v110, 16, v61
	v_and_b32_e32 v111, 0xffff0000, v61
	v_lshlrev_b32_e32 v102, 16, v49
	v_and_b32_e32 v103, 0xffff0000, v49
	v_pk_mul_f32 v[114:115], v[18:19], v[108:109]
	v_pk_fma_f32 v[112:113], v[26:27], v[110:111], v[196:197]
	v_pk_mul_f32 v[94:95], v[62:63], v[114:115] op_sel_hi:[0,1]
	v_pk_mul_f32 v[78:79], v[112:113], v[108:109]
	v_pk_mul_f32 v[86:87], v[94:95], v[110:111]
	v_lshlrev_b32_e32 v104, 16, v63
	v_and_b32_e32 v105, 0xffff0000, v63
	s_waitcnt lgkmcnt(0)
	v_add_f32_e32 v125, v124, v125
	v_add_f32_e32 v126, v125, v126
	v_add_f32_e32 v127, v126, v127
	v_add_f32_e32 v128, v127, v128
	v_add_f32_e32 v129, v128, v129
	v_add_f32_e32 v130, v129, v130
	v_add_f32_e32 v131, v130, v131
	s_and_b32 s72, s6, 3
	s_lshl_b32 s72, s72, 10
	v_add_u32_e32 v182, s72, v180
	v_add_u32_e32 v183, s72, v175
	v_add_u32_e32 v184, 1, v146
	s_add_u32 s73, s6, 1
	s_mov_b32 s69, 0x100000

.Lsc_gf_go4:
	ds_read_b32 v185, v183
	s_waitcnt lgkmcnt(0)
	v_and_b32_e32 v185, v174, v185
	v_fma_f32 v189, v131, s14, v185
	ds_write_b32 v182, v189
	s_waitcnt lgkmcnt(0)
	ds_write_b32 v162, v184
	v_fma_f32 v124, v124, s14, v185
	v_fma_f32 v125, v125, s14, v185
	v_fma_f32 v126, v126, s14, v185
	v_fma_f32 v127, v127, s14, v185
	v_fma_f32 v128, v128, s14, v185
	v_fma_f32 v129, v129, s14, v185
	v_fma_f32 v130, v130, s14, v185
	v_fma_f32 v131, v131, s14, v185
	v_exp_f32_e64 v188, -v185
	v_exp_f32_e64 v124, -v124
	v_exp_f32_e64 v125, -v125
	v_exp_f32_e64 v126, -v126
	v_exp_f32_e64 v127, -v127
	v_exp_f32_e64 v128, -v128
	v_exp_f32_e64 v129, -v129
	v_exp_f32_e64 v130, -v130
	v_exp_f32_e64 v131, -v131
	s_nop 0
	ds_write_b32 v155, v188
	ds_write_b32 v155, v124 offset:256
	ds_write_b32 v155, v125 offset:512
	ds_write_b32 v155, v126 offset:768
	ds_write_b32 v155, v127 offset:1024
	ds_write_b32 v155, v128 offset:1280
	ds_write_b32 v155, v129 offset:1536
	ds_write_b32 v155, v130 offset:1792
	ds_write_b32 v155, v131 offset:2048
	v_mov_b32_e32 v161, v131
	s_waitcnt lgkmcnt(0)
	ds_read_b128 v[64:67], v153 offset:2048
	ds_read_b128 v[68:71], v153 offset:2176
	ds_read_b128 v[116:119], v153 offset:2304
	ds_read_b128 v[120:123], v153 offset:2432
	s_waitcnt lgkmcnt(0)
	v_rcp_f32_e32 v124, v116
	v_rcp_f32_e32 v125, v117
	v_rcp_f32_e32 v126, v118
	v_rcp_f32_e32 v127, v119
	v_rcp_f32_e32 v128, v120
	v_rcp_f32_e32 v129, v121
	v_rcp_f32_e32 v130, v122
	v_rcp_f32_e32 v131, v123
	s_nop 1
	v_pk_mul_f32 v[72:73], v[72:73], v[124:125]
	v_pk_mul_f32 v[80:81], v[80:81], v[124:125]
	v_pk_mul_f32 v[88:89], v[88:89], v[64:65]
	v_pk_mul_f32 v[96:97], v[96:97], v[116:117]
	v_pk_mul_f32 v[74:75], v[74:75], v[126:127]
	v_pk_mul_f32 v[82:83], v[82:83], v[126:127]
	v_pk_mul_f32 v[90:91], v[90:91], v[66:67]
	v_pk_mul_f32 v[98:99], v[98:99], v[118:119]
	v_pk_mul_f32 v[76:77], v[76:77], v[128:129]
	v_pk_mul_f32 v[84:85], v[84:85], v[128:129]
	v_pk_mul_f32 v[92:93], v[92:93], v[68:69]
	v_pk_mul_f32 v[100:101], v[100:101], v[120:121]
	v_pk_mul_f32 v[78:79], v[78:79], v[130:131]
	v_pk_mul_f32 v[86:87], v[86:87], v[130:131]
	v_pk_mul_f32 v[94:95], v[94:95], v[70:71]
	v_pk_mul_f32 v[102:103], v[102:103], v[122:123]
	global_load_dwordx2 v[46:47], v5, s[36:37]
	global_load_dwordx2 v[48:49], v5, s[36:37] offset:64
	global_load_dwordx2 v[50:51], v5, s[38:39]
	global_load_dwordx2 v[52:53], v5, s[38:39] offset:64
	global_load_dwordx2 v[54:55], v5, s[40:41]
	global_load_dwordx2 v[56:57], v5, s[40:41] offset:64
	global_load_dwordx2 v[58:59], v5, s[42:43]
	global_load_dwordx2 v[60:61], v5, s[42:43] offset:64
	global_load_dword v62, v6, s[46:47]
	global_load_dword v63, v9, s[44:45]
	v_add_u32_e32 v5, s54, v5
	v_add_u32_e32 v6, s55, v6
	v_add_u32_e32 v9, s54, v9
	s_sub_u32 s65, s6, 1
	ds_read_b128 v[148:151], v144
	s_waitcnt lgkmcnt(0)
	v_min_u32_e32 v148, v148, v149
	v_min3_u32 v148, v148, v150, v151
	s_nop 1
	v_readfirstlane_b32 s68, v148
	s_cmp_ge_u32 s68, s65
	s_cbranch_scc1 .Lsc_G_gom1
	s_mov_b32 s69, 0x100000

.Lsc_nokb4:
	ds_read_b128 v[106:109], v2 offset:32768
	ds_read_b128 v[122:125], v2 offset:49152
	s_sleep 1
	ds_read_b128 v[110:113], v3 offset:32768
	ds_read_b128 v[126:129], v3 offset:49152
	s_sleep 1
	ds_read_b128 v[114:117], v4 offset:32768
	ds_read_b128 v[130:133], v4 offset:49152
	s_sleep 1
	ds_read_b128 v[118:121], v10 offset:32768
	ds_read_b128 v[134:137], v10 offset:49152
	s_sleep 1
	s_waitcnt lgkmcnt(0)
	v_pk_add_f32 v[106:107], v[106:107], v[108:109]
	v_pk_add_f32 v[110:111], v[110:111], v[112:113]
	v_pk_add_f32 v[114:115], v[114:115], v[116:117]
	v_pk_add_f32 v[118:119], v[118:119], v[120:121]
	v_pk_add_f32 v[106:107], v[106:107], v[110:111]
	v_pk_add_f32 v[114:115], v[114:115], v[118:119]
	v_pk_add_f32 v[106:107], v[106:107], v[114:115]
	v_add_f32_e32 v64, v106, v107
	v_pk_add_f32 v[122:123], v[122:123], v[124:125]
	v_pk_add_f32 v[126:127], v[126:127], v[128:129]
	v_pk_add_f32 v[130:131], v[130:131], v[132:133]
	v_pk_add_f32 v[134:135], v[134:135], v[136:137]
	v_pk_add_f32 v[122:123], v[122:123], v[126:127]
	v_pk_add_f32 v[130:131], v[130:131], v[134:135]
	v_pk_add_f32 v[122:123], v[122:123], v[130:131]
	v_add_f32_e32 v65, v122, v123
	global_store_dword v7, v64, s[48:49]
	global_store_dword v165, v65, s[48:49]
	v_add_u32_e32 v7, s64, v7
	v_add_u32_e32 v165, s64, v165
	s_add_i32 s6, s6, 1
	v_add_u32_e32 v146, 1, v146
	s_waitcnt lgkmcnt(0)
	ds_write_b32 v145, v146
	s_cmp_lt_u32 s6, 0xfe
	s_cbranch_scc1 .Lsc_G_loop
	s_waitcnt vmcnt(10)
	v_lshlrev_b32_e32 v64, 16, v36
	v_and_b32_e32 v65, 0xffff0000, v36
	v_lshlrev_b32_e32 v66, 16, v37
	v_and_b32_e32 v67, 0xffff0000, v37
	v_lshlrev_b32_e32 v68, 16, v38
	v_and_b32_e32 v69, 0xffff0000, v38
	v_lshlrev_b32_e32 v70, 16, v39
	v_and_b32_e32 v71, 0xffff0000, v39
	ds_write_b128 v153, v[64:67]
	ds_write_b128 v153, v[68:71] offset:128
	s_waitcnt lgkmcnt(0)
	ds_read_b32 v124, v154 offset:0
	ds_read_b32 v125, v154 offset:256
	ds_read_b32 v126, v154 offset:512
	ds_read_b32 v127, v154 offset:768
	ds_read_b32 v128, v154 offset:1024
	ds_read_b32 v129, v154 offset:1280
	ds_read_b32 v130, v154 offset:1536
	ds_read_b32 v131, v154 offset:1792
	v_lshlrev_b32_e32 v108, 16, v32
	v_and_b32_e32 v109, 0xffff0000, v32
	v_lshlrev_b32_e32 v110, 16, v40
	v_and_b32_e32 v111, 0xffff0000, v40
	v_lshlrev_b32_e32 v96, 16, v28
	v_and_b32_e32 v97, 0xffff0000, v28
	v_pk_mul_f32 v[114:115], v[12:13], v[108:109]
	v_pk_fma_f32 v[112:113], v[20:21], v[110:111], v[190:191]
	v_pk_mul_f32 v[88:89], v[44:45], v[114:115] op_sel_hi:[0,1]
	v_pk_mul_f32 v[72:73], v[112:113], v[108:109]
	v_pk_mul_f32 v[80:81], v[88:89], v[110:111]
	v_lshlrev_b32_e32 v108, 16, v33
	v_and_b32_e32 v109, 0xffff0000, v33
	v_lshlrev_b32_e32 v110, 16, v41
	v_and_b32_e32 v111, 0xffff0000, v41
	v_lshlrev_b32_e32 v98, 16, v29
	v_and_b32_e32 v99, 0xffff0000, v29
	v_pk_mul_f32 v[114:115], v[14:15], v[108:109]
	v_pk_fma_f32 v[112:113], v[22:23], v[110:111], v[192:193]
	v_pk_mul_f32 v[90:91], v[44:45], v[114:115] op_sel_hi:[0,1]
	v_pk_mul_f32 v[74:75], v[112:113], v[108:109]
	v_pk_mul_f32 v[82:83], v[90:91], v[110:111]
	v_lshlrev_b32_e32 v108, 16, v34
	v_and_b32_e32 v109, 0xffff0000, v34
	v_lshlrev_b32_e32 v110, 16, v42
	v_and_b32_e32 v111, 0xffff0000, v42
	v_lshlrev_b32_e32 v100, 16, v30
	v_and_b32_e32 v101, 0xffff0000, v30
	v_pk_mul_f32 v[114:115], v[16:17], v[108:109]
	v_pk_fma_f32 v[112:113], v[24:25], v[110:111], v[194:195]
	v_pk_mul_f32 v[92:93], v[44:45], v[114:115] op_sel_hi:[0,1]
	v_pk_mul_f32 v[76:77], v[112:113], v[108:109]
	v_pk_mul_f32 v[84:85], v[92:93], v[110:111]
	v_lshlrev_b32_e32 v108, 16, v35
	v_and_b32_e32 v109, 0xffff0000, v35
	v_lshlrev_b32_e32 v110, 16, v43
	v_and_b32_e32 v111, 0xffff0000, v43
	v_lshlrev_b32_e32 v102, 16, v31
	v_and_b32_e32 v103, 0xffff0000, v31
	v_pk_mul_f32 v[114:115], v[18:19], v[108:109]
	v_pk_fma_f32 v[112:113], v[26:27], v[110:111], v[196:197]
	v_pk_mul_f32 v[94:95], v[44:45], v[114:115] op_sel_hi:[0,1]
	v_pk_mul_f32 v[78:79], v[112:113], v[108:109]
	v_pk_mul_f32 v[86:87], v[94:95], v[110:111]
	v_lshlrev_b32_e32 v104, 16, v45
	v_and_b32_e32 v105, 0xffff0000, v45
	s_waitcnt lgkmcnt(0)
	v_add_f32_e32 v125, v124, v125
	v_add_f32_e32 v126, v125, v126
	v_add_f32_e32 v127, v126, v127
	v_add_f32_e32 v128, v127, v128
	v_add_f32_e32 v129, v128, v129
	v_add_f32_e32 v130, v129, v130
	v_add_f32_e32 v131, v130, v131
	s_and_b32 s72, s6, 3
	s_lshl_b32 s72, s72, 10
	v_add_u32_e32 v182, s72, v180
	v_add_u32_e32 v183, s72, v175
	v_add_u32_e32 v184, 1, v146
	s_add_u32 s73, s6, 1
	s_mov_b32 s69, 0x100000

.Lsc_gf_go5:
	ds_read_b32 v185, v183
	s_waitcnt lgkmcnt(0)
	v_and_b32_e32 v185, v174, v185
	v_fma_f32 v189, v131, s14, v185
	ds_write_b32 v182, v189
	s_waitcnt lgkmcnt(0)
	ds_write_b32 v162, v184
	v_fma_f32 v124, v124, s14, v185
	v_fma_f32 v125, v125, s14, v185
	v_fma_f32 v126, v126, s14, v185
	v_fma_f32 v127, v127, s14, v185
	v_fma_f32 v128, v128, s14, v185
	v_fma_f32 v129, v129, s14, v185
	v_fma_f32 v130, v130, s14, v185
	v_fma_f32 v131, v131, s14, v185
	v_exp_f32_e64 v188, -v185
	v_exp_f32_e64 v124, -v124
	v_exp_f32_e64 v125, -v125
	v_exp_f32_e64 v126, -v126
	v_exp_f32_e64 v127, -v127
	v_exp_f32_e64 v128, -v128
	v_exp_f32_e64 v129, -v129
	v_exp_f32_e64 v130, -v130
	v_exp_f32_e64 v131, -v131
	s_nop 0
	ds_write_b32 v155, v188
	ds_write_b32 v155, v124 offset:256
	ds_write_b32 v155, v125 offset:512
	ds_write_b32 v155, v126 offset:768
	ds_write_b32 v155, v127 offset:1024
	ds_write_b32 v155, v128 offset:1280
	ds_write_b32 v155, v129 offset:1536
	ds_write_b32 v155, v130 offset:1792
	ds_write_b32 v155, v131 offset:2048
	v_mov_b32_e32 v161, v131
	s_waitcnt lgkmcnt(0)
	ds_read_b128 v[64:67], v153 offset:2048
	ds_read_b128 v[68:71], v153 offset:2176
	ds_read_b128 v[116:119], v153 offset:2304
	ds_read_b128 v[120:123], v153 offset:2432
	s_waitcnt lgkmcnt(0)
	v_rcp_f32_e32 v124, v116
	v_rcp_f32_e32 v125, v117
	v_rcp_f32_e32 v126, v118
	v_rcp_f32_e32 v127, v119
	v_rcp_f32_e32 v128, v120
	v_rcp_f32_e32 v129, v121
	v_rcp_f32_e32 v130, v122
	v_rcp_f32_e32 v131, v123
	s_nop 1
	v_pk_mul_f32 v[72:73], v[72:73], v[124:125]
	v_pk_mul_f32 v[80:81], v[80:81], v[124:125]
	v_pk_mul_f32 v[88:89], v[88:89], v[64:65]
	v_pk_mul_f32 v[96:97], v[96:97], v[116:117]
	v_pk_mul_f32 v[74:75], v[74:75], v[126:127]
	v_pk_mul_f32 v[82:83], v[82:83], v[126:127]
	v_pk_mul_f32 v[90:91], v[90:91], v[66:67]
	v_pk_mul_f32 v[98:99], v[98:99], v[118:119]
	v_pk_mul_f32 v[76:77], v[76:77], v[128:129]
	v_pk_mul_f32 v[84:85], v[84:85], v[128:129]
	v_pk_mul_f32 v[92:93], v[92:93], v[68:69]
	v_pk_mul_f32 v[100:101], v[100:101], v[120:121]
	v_pk_mul_f32 v[78:79], v[78:79], v[130:131]
	v_pk_mul_f32 v[86:87], v[86:87], v[130:131]
	v_pk_mul_f32 v[94:95], v[94:95], v[70:71]
	v_pk_mul_f32 v[102:103], v[102:103], v[122:123]
	s_sub_u32 s65, s6, 1
	ds_read_b128 v[148:151], v144
	s_waitcnt lgkmcnt(0)
	v_min_u32_e32 v148, v148, v149
	v_min3_u32 v148, v148, v150, v151
	s_nop 1
	v_readfirstlane_b32 s68, v148
	s_cmp_ge_u32 s68, s65
	s_cbranch_scc1 .Lsc_G_goz0
	s_mov_b32 s69, 0x100000

.Lsc_nokb5:
	ds_read_b128 v[106:109], v2 offset:0
	ds_read_b128 v[122:125], v2 offset:16384
	s_sleep 1
	ds_read_b128 v[110:113], v3 offset:0
	ds_read_b128 v[126:129], v3 offset:16384
	s_sleep 1
	ds_read_b128 v[114:117], v4 offset:0
	ds_read_b128 v[130:133], v4 offset:16384
	s_sleep 1
	ds_read_b128 v[118:121], v10 offset:0
	ds_read_b128 v[134:137], v10 offset:16384
	s_sleep 1
	s_waitcnt lgkmcnt(0)
	v_pk_add_f32 v[106:107], v[106:107], v[108:109]
	v_pk_add_f32 v[110:111], v[110:111], v[112:113]
	v_pk_add_f32 v[114:115], v[114:115], v[116:117]
	v_pk_add_f32 v[118:119], v[118:119], v[120:121]
	v_pk_add_f32 v[106:107], v[106:107], v[110:111]
	v_pk_add_f32 v[114:115], v[114:115], v[118:119]
	v_pk_add_f32 v[106:107], v[106:107], v[114:115]
	v_add_f32_e32 v64, v106, v107
	v_pk_add_f32 v[122:123], v[122:123], v[124:125]
	v_pk_add_f32 v[126:127], v[126:127], v[128:129]
	v_pk_add_f32 v[130:131], v[130:131], v[132:133]
	v_pk_add_f32 v[134:135], v[134:135], v[136:137]
	v_pk_add_f32 v[122:123], v[122:123], v[126:127]
	v_pk_add_f32 v[130:131], v[130:131], v[134:135]
	v_pk_add_f32 v[122:123], v[122:123], v[130:131]
	v_add_f32_e32 v65, v122, v123
	global_store_dword v7, v64, s[48:49]
	global_store_dword v165, v65, s[48:49]
	v_add_u32_e32 v7, s64, v7
	v_add_u32_e32 v165, s64, v165
	s_add_i32 s6, s6, 1
	v_add_u32_e32 v146, 1, v146
	s_waitcnt lgkmcnt(0)
	ds_write_b32 v145, v146
	s_waitcnt vmcnt(0)
	v_lshlrev_b32_e32 v64, 16, v54
	v_and_b32_e32 v65, 0xffff0000, v54
	v_lshlrev_b32_e32 v66, 16, v55
	v_and_b32_e32 v67, 0xffff0000, v55
	v_lshlrev_b32_e32 v68, 16, v56
	v_and_b32_e32 v69, 0xffff0000, v56
	v_lshlrev_b32_e32 v70, 16, v57
	v_and_b32_e32 v71, 0xffff0000, v57
	ds_write_b128 v153, v[64:67]
	ds_write_b128 v153, v[68:71] offset:128
	s_waitcnt lgkmcnt(0)
	ds_read_b32 v124, v154 offset:0
	ds_read_b32 v125, v154 offset:256
	ds_read_b32 v126, v154 offset:512
	ds_read_b32 v127, v154 offset:768
	ds_read_b32 v128, v154 offset:1024
	ds_read_b32 v129, v154 offset:1280
	ds_read_b32 v130, v154 offset:1536
	ds_read_b32 v131, v154 offset:1792
	v_lshlrev_b32_e32 v108, 16, v50
	v_and_b32_e32 v109, 0xffff0000, v50
	v_lshlrev_b32_e32 v110, 16, v58
	v_and_b32_e32 v111, 0xffff0000, v58
	v_lshlrev_b32_e32 v96, 16, v46
	v_and_b32_e32 v97, 0xffff0000, v46
	v_pk_mul_f32 v[114:115], v[12:13], v[108:109]
	v_pk_fma_f32 v[112:113], v[20:21], v[110:111], v[190:191]
	v_pk_mul_f32 v[88:89], v[62:63], v[114:115] op_sel_hi:[0,1]
	v_pk_mul_f32 v[72:73], v[112:113], v[108:109]
	v_pk_mul_f32 v[80:81], v[88:89], v[110:111]
	v_lshlrev_b32_e32 v108, 16, v51
	v_and_b32_e32 v109, 0xffff0000, v51
	v_lshlrev_b32_e32 v110, 16, v59
	v_and_b32_e32 v111, 0xffff0000, v59
	v_lshlrev_b32_e32 v98, 16, v47
	v_and_b32_e32 v99, 0xffff0000, v47
	v_pk_mul_f32 v[114:115], v[14:15], v[108:109]
	v_pk_fma_f32 v[112:113], v[22:23], v[110:111], v[192:193]
	v_pk_mul_f32 v[90:91], v[62:63], v[114:115] op_sel_hi:[0,1]
	v_pk_mul_f32 v[74:75], v[112:113], v[108:109]
	v_pk_mul_f32 v[82:83], v[90:91], v[110:111]
	v_lshlrev_b32_e32 v108, 16, v52
	v_and_b32_e32 v109, 0xffff0000, v52
	v_lshlrev_b32_e32 v110, 16, v60
	v_and_b32_e32 v111, 0xffff0000, v60
	v_lshlrev_b32_e32 v100, 16, v48
	v_and_b32_e32 v101, 0xffff0000, v48
	v_pk_mul_f32 v[114:115], v[16:17], v[108:109]
	v_pk_fma_f32 v[112:113], v[24:25], v[110:111], v[194:195]
	v_pk_mul_f32 v[92:93], v[62:63], v[114:115] op_sel_hi:[0,1]
	v_pk_mul_f32 v[76:77], v[112:113], v[108:109]
	v_pk_mul_f32 v[84:85], v[92:93], v[110:111]
	v_lshlrev_b32_e32 v108, 16, v53
	v_and_b32_e32 v109, 0xffff0000, v53
	v_lshlrev_b32_e32 v110, 16, v61
	v_and_b32_e32 v111, 0xffff0000, v61
	v_lshlrev_b32_e32 v102, 16, v49
	v_and_b32_e32 v103, 0xffff0000, v49
	v_pk_mul_f32 v[114:115], v[18:19], v[108:109]
	v_pk_fma_f32 v[112:113], v[26:27], v[110:111], v[196:197]
	v_pk_mul_f32 v[94:95], v[62:63], v[114:115] op_sel_hi:[0,1]
	v_pk_mul_f32 v[78:79], v[112:113], v[108:109]
	v_pk_mul_f32 v[86:87], v[94:95], v[110:111]
	v_lshlrev_b32_e32 v104, 16, v63
	v_and_b32_e32 v105, 0xffff0000, v63
	s_waitcnt lgkmcnt(0)
	v_add_f32_e32 v125, v124, v125
	v_add_f32_e32 v126, v125, v126
	v_add_f32_e32 v127, v126, v127
	v_add_f32_e32 v128, v127, v128
	v_add_f32_e32 v129, v128, v129
	v_add_f32_e32 v130, v129, v130
	v_add_f32_e32 v131, v130, v131
	s_and_b32 s72, s6, 3
	s_lshl_b32 s72, s72, 10
	v_add_u32_e32 v182, s72, v180
	v_add_u32_e32 v183, s72, v175
	v_add_u32_e32 v184, 1, v146
	s_add_u32 s73, s6, 1
	s_mov_b32 s69, 0x100000
